# ResNorm panel-counter poll: s_sleep 2 between polls reduced to s_sleep 0
# speedup vs baseline: 1.0048x; 1.0048x over previous
;     __device__ __forceinline__ void operator()(f32x4 (&acc)[2][2][4][2], const Unit& u, int wr, int wc, int fr, int fq) const {
;     ...
;         if (wr == 0 && wc == 0) {
;             unsigned sp = 0u;
;             while ((unsigned)__builtin_amdgcn_readfirstlane(__hip_atomic_load(cnt + 64 * u.pm, __ATOMIC_RELAXED, __HIP_MEMORY_SCOPE_AGENT)) < 64u) { __builtin_amdgcn_s_sleep(2); if (++sp > (1u << 21)) break; }
;             __builtin_amdgcn_fence(__ATOMIC_ACQUIRE, "agent");
;         }
.LBB0_317:
	global_load_dword v130, v1, s[46:47] sc1
	s_waitcnt vmcnt(0)
	v_readfirstlane_b32 s70, v130
	s_cmp_gt_u32 s70, 63
	s_mov_b64 s[70:71], -1
	s_cbranch_scc1 .LBB0_316
	s_sleep 0
	global_load_dword v130, v1, s[46:47] sc1
	s_waitcnt vmcnt(0)
	v_readfirstlane_b32 s70, v130
	s_cmp_lt_u32 s70, 64
	s_mov_b64 s[70:71], -1
	s_cbranch_scc0 .LBB0_316
	s_sleep 0
	global_load_dword v130, v1, s[46:47] sc1
	s_waitcnt vmcnt(0)
	v_readfirstlane_b32 s70, v130
	s_cmp_lt_u32 s70, 64
	s_mov_b64 s[70:71], -1
	s_cbranch_scc0 .LBB0_316
	s_sleep 0
	global_load_dword v130, v1, s[46:47] sc1
	s_waitcnt vmcnt(0)
	v_readfirstlane_b32 s70, v130
	s_cmp_lt_u32 s70, 64
	s_mov_b64 s[70:71], -1
	s_cbranch_scc0 .LBB0_316
	s_sleep 0
	global_load_dword v130, v1, s[46:47] sc1
	s_waitcnt vmcnt(0)
	v_readfirstlane_b32 s70, v130
	s_cmp_lt_u32 s70, 64
	s_mov_b64 s[70:71], -1
	s_cbranch_scc0 .LBB0_316
	s_sleep 0
	global_load_dword v130, v1, s[46:47] sc1
	s_waitcnt vmcnt(0)
	v_readfirstlane_b32 s70, v130
	s_cmp_lt_u32 s70, 64
	s_mov_b64 s[70:71], -1
	s_cbranch_scc0 .LBB0_316
	s_sleep 0
	global_load_dword v130, v1, s[46:47] sc1
	s_waitcnt vmcnt(0)
	v_readfirstlane_b32 s70, v130
	s_cmp_lt_u32 s70, 64
	s_mov_b64 s[70:71], -1
	s_cbranch_scc0 .LBB0_316
	s_sleep 0
	global_load_dword v130, v1, s[46:47] sc1
	s_waitcnt vmcnt(0)
	v_readfirstlane_b32 s70, v130
	s_cmp_lt_u32 s70, 64
	s_mov_b64 s[70:71], -1
	s_cbranch_scc0 .LBB0_316
	s_sleep 0
	global_load_dword v130, v1, s[46:47] sc1
	s_waitcnt vmcnt(0)
	v_readfirstlane_b32 s70, v130
	s_cmp_lt_u32 s70, 64
	s_mov_b64 s[70:71], -1
	s_cbranch_scc0 .LBB0_316
	s_add_i32 s72, s72, -9
	s_cmp_eq_u32 s72, 0
	s_cselect_b64 s[70:71], -1, 0
	s_sleep 0
	s_branch .LBB0_316

;     __device__ __forceinline__ void operator()(f32x4 (&acc)[2][2][4][2], const Unit& u, int wr, int wc, int fr, int fq) const {
;     ...
;         if (wr == 0 && wc == 0) {
;             unsigned sp = 0u;
;             while ((unsigned)__builtin_amdgcn_readfirstlane(__hip_atomic_load(cnt + 64 * u.pm, __ATOMIC_RELAXED, __HIP_MEMORY_SCOPE_AGENT)) < 64u) { __builtin_amdgcn_s_sleep(2); if (++sp > (1u << 21)) break; }
;             __builtin_amdgcn_fence(__ATOMIC_ACQUIRE, "agent");
;         }
.LBB0_364:
	global_load_dword v2, v1, s[44:45] sc1
	s_waitcnt vmcnt(0)
	v_readfirstlane_b32 s62, v2
	s_cmp_gt_u32 s62, 63
	s_mov_b64 s[62:63], -1
	s_cbranch_scc1 .LBB0_363
	s_sleep 0
	global_load_dword v2, v1, s[44:45] sc1
	s_waitcnt vmcnt(0)
	v_readfirstlane_b32 s62, v2
	s_cmp_lt_u32 s62, 64
	s_mov_b64 s[62:63], -1
	s_cbranch_scc0 .LBB0_363
	s_sleep 0
	global_load_dword v2, v1, s[44:45] sc1
	s_waitcnt vmcnt(0)
	v_readfirstlane_b32 s62, v2
	s_cmp_lt_u32 s62, 64
	s_mov_b64 s[62:63], -1
	s_cbranch_scc0 .LBB0_363
	s_sleep 0
	global_load_dword v2, v1, s[44:45] sc1
	s_waitcnt vmcnt(0)
	v_readfirstlane_b32 s62, v2
	s_cmp_lt_u32 s62, 64
	s_mov_b64 s[62:63], -1
	s_cbranch_scc0 .LBB0_363
	s_sleep 0
	global_load_dword v2, v1, s[44:45] sc1
	s_waitcnt vmcnt(0)
	v_readfirstlane_b32 s62, v2
	s_cmp_lt_u32 s62, 64
	s_mov_b64 s[62:63], -1
	s_cbranch_scc0 .LBB0_363
	s_sleep 0
	global_load_dword v2, v1, s[44:45] sc1
	s_waitcnt vmcnt(0)
	v_readfirstlane_b32 s62, v2
	s_cmp_lt_u32 s62, 64
	s_mov_b64 s[62:63], -1
	s_cbranch_scc0 .LBB0_363
	s_sleep 0
	global_load_dword v2, v1, s[44:45] sc1
	s_waitcnt vmcnt(0)
	v_readfirstlane_b32 s62, v2
	s_cmp_lt_u32 s62, 64
	s_mov_b64 s[62:63], -1
	s_cbranch_scc0 .LBB0_363
	s_sleep 0
	global_load_dword v2, v1, s[44:45] sc1
	s_waitcnt vmcnt(0)
	v_readfirstlane_b32 s62, v2
	s_cmp_lt_u32 s62, 64
	s_mov_b64 s[62:63], -1
	s_cbranch_scc0 .LBB0_363
	s_sleep 0
	global_load_dword v2, v1, s[44:45] sc1
	s_waitcnt vmcnt(0)
	v_readfirstlane_b32 s62, v2
	s_cmp_lt_u32 s62, 64
	s_mov_b64 s[62:63], -1
	s_cbranch_scc0 .LBB0_363
	s_add_i32 s64, s64, -9
	s_cmp_eq_u32 s64, 0
	s_cselect_b64 s[62:63], -1, 0
	s_sleep 0
	s_branch .LBB0_363
